# P1: workgroup groups start 0/1.5/3/4.5 us apart so the per-round epilogue store bursts interleave
# speedup vs baseline: 1.0138x; 1.0138x over previous
; DEVINL void phase1(const Params& p) {
;     ...
;   for (int t = blockIdx.x; t < ntiles; t += gridDim.x) {
;     int pm = t & 31, pn = t >> 5;
;     gemm_tile<EPI_COLS, false>(p, A, 2048, nullptr, Bt, 2048, 2048, pm * 256, pn * 256, pm * 256, pn * 256);
;   }
.Lq_p1entry:
	s_andn2_b64 vcc, exec, s[58:59]
	s_waitcnt lgkmcnt(0)
	s_barrier
	s_cbranch_vccnz .LBB0_231
	s_cmp_eq_u32 s98, 1
	s_cbranch_scc1 .Lstag_done
	s_bfe_u32 s6, s2, 0x20003
	s_cmp_eq_u32 s6, 0
	s_cbranch_scc1 .Lstag_done
.Lstag_loop:
	s_sleep 48
	s_sub_u32 s6, s6, 1
	s_cmp_lg_u32 s6, 0
	s_cbranch_scc1 .Lstag_loop
.Lstag_done:
	s_add_u32 s0, s92, 0x4c00000
	s_mov_b64 s[56:57], s[96:97]
	s_addc_u32 s1, s93, 0
	s_lshl_b32 s3, s2, 8
	s_lshl_b32 s40, s94, 8
	s_lshl_b32 s41, s2, 3
	s_lshl_b32 s42, s94, 3
	s_mov_b32 s5, 0
	s_add_i32 s43, 16, 0x10000
	s_add_i32 s44, 16, 0x14000
	s_add_i32 s45, 16, 0x18000
	s_mov_b64 s[8:9], 0x80
	s_add_i32 s46, 16, 0x1c000
	s_mov_b64 s[18:19], 0x80080
	s_mov_b64 s[22:23], 0x2000100
	s_mov_b64 s[24:25], 0x100
	s_mov_b64 s[36:37], 0x2080100
	s_mov_b64 s[38:39], 0x80100
	s_mov_b64 s[68:69], 0x2000180
	s_mov_b64 s[70:71], 0x180
	s_mov_b64 s[72:73], 0x2080180
	v_mov_b32_e32 v140, 1
	s_mov_b32 s47, s2
	s_branch .LBB0_224
